# P5/P6 start stagger: odd XCDs s_sleep 32 (~1.2 us) late
# speedup vs baseline: 1.0044x; 1.0044x over previous
; #define LAS __attribute__((address_space(3)))
;     DI bool next(int i, Unit& u) const {
;         const long L = (long)i * G + c; if (L >= nwg) return false;
;         int wgid = (int)L; { const int q = nwg / NXCD, r = nwg % NXCD, xcd = wgid % NXCD, off = wgid / NXCD; wgid = (xcd < r ? xcd * (q + 1) : r * (q + 1) + (xcd - r) * q) + off; }
;         const int nig = WGM * nN, gid = wgid / nig, fm = gid * WGM, gsz = (nM - fm) < WGM ? (nM - fm) : WGM;
;         u.pm = fm + ((wgid % nig) % gsz); u.pn = (wgid % nig) / gsz; return true;
; __global__ void __launch_bounds__(512, 2) mega(Params p) {
;     ...
;     if (PH(5)) {
;         pg8::Gemm g; g.A0 = (const bf16_t*)(p.ws + WS_ZG); g.A1 = (const bf16_t*)(p.ws + WS_YB) - 2048; g.B0 = (const bf16_t*)(p.ws + WS_WAT); g.B1 = (const bf16_t*)(p.ws + WS_WBT) - 2048;
;         g.lda = DM; g.ldb = DM; g.M = S; g.N = DM; g.K = 2 * DM; g.ksplit = DM / 64;
;         pg8::StaticOrder so; so.init(g.M, g.N, (int)gridDim.x, (int)blockIdx.x);
;         EpiMergeMid e; e.ws = p.ws;
;         pg8::gemm_phase<EpiMergeMid>((LAS unsigned char*)shm, g, so, e);
.LBB0_431:
	s_or_b64 exec, exec, s[4:5]
	v_cmp_gt_i32_e32 vcc, 6, v0
	v_cmp_lt_i32_e64 s[4:5], 5, v1
	s_and_b64 s[4:5], vcc, s[4:5]
	s_and_saveexec_b64 s[6:7], s[4:5]
	s_cbranch_execz .LBB0_456
	s_bitcmp1_b32 s2, 0
	s_cbranch_scc0 .Lp5_nostag
	s_sleep 32

; #define LAS __attribute__((address_space(3)))
;     DI bool next(int i, Unit& u) const {
;         const long L = (long)i * G + c; if (L >= nwg) return false;
;         int wgid = (int)L; { const int q = nwg / NXCD, r = nwg % NXCD, xcd = wgid % NXCD, off = wgid / NXCD; wgid = (xcd < r ? xcd * (q + 1) : r * (q + 1) + (xcd - r) * q) + off; }
;         const int nig = WGM * nN, gid = wgid / nig, fm = gid * WGM, gsz = (nM - fm) < WGM ? (nM - fm) : WGM;
;         u.pm = fm + ((wgid % nig) % gsz); u.pn = (wgid % nig) / gsz; return true;
; __global__ void __launch_bounds__(512, 2) mega(Params p) {
;     ...
;     if (PH(6)) {
;         pg8::Gemm g; g.A0 = (const bf16_t*)(p.ws + WS_MRG); g.A1 = g.A0; g.B0 = (const bf16_t*)(p.ws + WS_WOT); g.B1 = g.B0;
;         g.lda = DM; g.ldb = DM; g.M = S; g.N = DM; g.K = DM; g.ksplit = DM / 64;
;         pg8::StaticOrder so; so.init(g.M, g.N, (int)gridDim.x, (int)blockIdx.x);
;         EpiOut e; e.ws = p.ws;
;         pg8::gemm_phase<EpiOut>((LAS unsigned char*)shm, g, so, e);
.LBB0_506:
	s_or_b64 exec, exec, s[4:5]
	v_cmp_gt_i32_e32 vcc, 7, v0
	v_cmp_lt_i32_e64 s[4:5], 6, v1
	s_and_b64 s[4:5], vcc, s[4:5]
	s_and_saveexec_b64 s[8:9], s[4:5]
	s_cbranch_execz .LBB0_545
	s_bitcmp1_b32 s2, 0
	s_cbranch_scc0 .Lp6_nostag
	s_sleep 32
